# layer-1 in-proj seam is a team barrier again, plus a wait on the team counters of the (up to 3+3) panels whose act rows alias this team's proj panels (those teams must have finished down-proj)
# speedup vs baseline: 1.0020x; 1.0020x over previous
.Ltb_done:
	s_cmp_lg_u32 s80, 11
	s_cbranch_scc1 .Ltb_nodep
	v_readlane_b32 s6, v254, 44
	v_readlane_b32 s7, v254, 45
	s_bfe_u32 s13, s61, 0x60003
	s_and_b32 s14, s13, 7
	s_lshr_b32 s13, s13, 3
	s_lshl_b32 s15, s14, 4
	s_add_i32 s15, s15, s13
	s_add_i32 s2, s15, 8
	s_mul_i32 s16, s15, 31
	s_mul_i32 s17, s16, 0xba3
	s_lshr_b32 s17, s17, 16
	s_add_i32 s16, s16, 30
	s_mul_i32 s16, s16, 0xba3
	s_lshr_b32 s16, s16, 16
	s_min_u32 s16, s16, 0x7f
	s_add_i32 s20, s17, 0
	s_cmp_le_u32 s20, s16
	s_cselect_b32 s20, s20, s15
	s_lshr_b32 s3, s20, 4
	s_lshl_b32 s3, s3, 6
	s_and_b32 s20, s20, 7
	s_lshl_b32 s20, s20, 2
	s_add_i32 s20, s20, s3
	s_add_i32 s20, s20, 0x300
	v_mov_b32_e32 v5, s20
	s_add_i32 s20, s17, 1
	s_cmp_le_u32 s20, s16
	s_cselect_b32 s20, s20, s15
	s_lshr_b32 s3, s20, 4
	s_lshl_b32 s3, s3, 6
	s_and_b32 s20, s20, 7
	s_lshl_b32 s20, s20, 2
	s_add_i32 s20, s20, s3
	s_add_i32 s20, s20, 0x300
	v_mov_b32_e32 v6, s20
	s_add_i32 s20, s17, 2
	s_cmp_le_u32 s20, s16
	s_cselect_b32 s20, s20, s15
	s_lshr_b32 s3, s20, 4
	s_lshl_b32 s3, s3, 6
	s_and_b32 s20, s20, 7
	s_lshl_b32 s20, s20, 2
	s_add_i32 s20, s20, s3
	s_add_i32 s20, s20, 0x300
	v_mov_b32_e32 v7, s20
	s_mul_i32 s16, s2, 31
	s_mul_i32 s17, s16, 0xba3
	s_lshr_b32 s17, s17, 16
	s_add_i32 s16, s16, 30
	s_mul_i32 s16, s16, 0xba3
	s_lshr_b32 s16, s16, 16
	s_min_u32 s16, s16, 0x7f
	s_add_i32 s20, s17, 0
	s_cmp_le_u32 s20, s16
	s_cselect_b32 s20, s20, s15
	s_lshr_b32 s3, s20, 4
	s_lshl_b32 s3, s3, 6
	s_and_b32 s20, s20, 7
	s_lshl_b32 s20, s20, 2
	s_add_i32 s20, s20, s3
	s_add_i32 s20, s20, 0x300
	v_mov_b32_e32 v8, s20
	s_add_i32 s20, s17, 1
	s_cmp_le_u32 s20, s16
	s_cselect_b32 s20, s20, s15
	s_lshr_b32 s3, s20, 4
	s_lshl_b32 s3, s3, 6
	s_and_b32 s20, s20, 7
	s_lshl_b32 s20, s20, 2
	s_add_i32 s20, s20, s3
	s_add_i32 s20, s20, 0x300
	v_mov_b32_e32 v9, s20
	s_add_i32 s20, s17, 2
	s_cmp_le_u32 s20, s16
	s_cselect_b32 s20, s20, s15
	s_lshr_b32 s3, s20, 4
	s_lshl_b32 s3, s3, 6
	s_and_b32 s20, s20, 7
	s_lshl_b32 s20, s20, 2
	s_add_i32 s20, s20, s3
	s_add_i32 s20, s20, 0x300
	v_mov_b32_e32 v10, s20
	s_mov_b32 s21, 0
.Ltb_dep:
	global_load_dword v11, v5, s[6:7] sc1
	global_load_dword v12, v6, s[6:7] sc1
	global_load_dword v13, v7, s[6:7] sc1
	global_load_dword v14, v8, s[6:7] sc1
	global_load_dword v15, v9, s[6:7] sc1
	global_load_dword v16, v10, s[6:7] sc1
	s_waitcnt vmcnt(0)
	v_min3_u32 v11, v11, v12, v13
	v_min3_u32 v11, v11, v14, v15
	v_min_u32_e32 v11, v11, v16
	v_readfirstlane_b32 s20, v11
	s_cmp_ge_u32 s20, 16
	s_cbranch_scc1 .Ltb_nodep
	s_add_i32 s21, s21, 1
	s_cmp_lt_u32 s21, 0x2000
	s_cbranch_scc1 .Ltb_dep
